# GDN scan: chain-to-block map changed so the 8 DV slices of one (batch,head) run on blocks of one XCD (shared W/Q/K/A tiles hit that XCD's L2)
# speedup vs baseline: 1.0189x; 1.0189x over previous
.LBB0_331:
	s_andn2_b64 vcc, exec, s[4:5]
	s_cbranch_vccnz .LBB0_753
	s_cmp_lt_i32 s90, 5
	s_cbranch_scc0 .LBB0_753
	v_readlane_b32 s4, v255, 20
	s_lshl_b32 s2, s4, 5
	s_lshl_b32 s4, s28, 4
	v_readlane_b32 s5, v255, 21
	s_add_i32 s4, s4, s2
	s_ashr_i32 s5, s4, 31
	s_lshl_b64 s[8:9], s[4:5], 2
	s_add_u32 s2, s44, s8
	s_addc_u32 s4, s45, s9
	s_add_u32 s19, s2, 0x1d504900
	s_addc_u32 s2, s4, 0
	v_writelane_b32 v255, s2, 26
	s_nop 0
	v_readlane_b32 s4, v255, 18
	v_readlane_b32 s5, v255, 19
	s_cmpk_gt_i32 s4, 0x7f
	v_writelane_b32 v255, s19, 27
	s_cbranch_scc1 .LBB0_569
	v_writelane_b32 v255, s8, 28
	s_waitcnt vmcnt(0)
	v_mov_b32_e32 v1, v228
	v_mov_b32_e32 v2, 0
	v_writelane_b32 v255, s9, 29
	v_writelane_b32 v255, s34, 30
	v_readfirstlane_b32 s12, v1
	s_ashr_i32 s13, s12, 6
	v_writelane_b32 v255, s35, 31
	v_lshlrev_b32_e32 v0, 3, v1
	v_readlane_b32 s4, v255, 18
	s_and_b32 s2, s4, 7
	s_lshl_b32 s2, s2, 4
	s_lshr_b32 s4, s4, 3
	s_or_b32 s4, s4, s2
	s_bfe_u32 s34, s4, 0x20003
	v_readlane_b32 s5, v255, 19
	s_ashr_i32 s37, s4, 5
	s_lshl_b32 s2, s4, 4
	s_lshl_b32 s17, s34, 8
	s_and_b32 s4, s2, 0x70
	s_lshl_b32 s35, s37, 12
	s_add_i32 s2, s13, -2
	s_lshl_b32 s5, s34, 7
	s_or_b32 s16, s17, 0x1e505000
	v_and_b32_e32 v3, 63, v1
	v_and_or_b32 v5, v0, 8, s5
	v_mov_b32_e32 v0, 0
	s_cmp_lt_u32 s2, 63
	s_cbranch_scc0 .LBB0_352
	s_lshl_b32 s18, s2, 6
	v_or_b32_e32 v4, s18, v3
	s_movk_i32 s8, 0x43f
	v_cmp_lt_i32_e32 vcc, s8, v4
	s_and_saveexec_b64 s[8:9], vcc
	s_xor_b64 s[8:9], exec, s[8:9]
	s_cbranch_execz .LBB0_349
	s_cmpk_gt_u32 s18, 0x87f
	s_mov_b64 s[14:15], -1
	s_cbranch_scc0 .LBB0_346
	s_cmpk_gt_u32 s18, 0xcff
	s_cbranch_scc0 .LBB0_343
	s_cmpk_gt_u32 s18, 0xf3f
	s_cbranch_scc0 .LBB0_340
	v_add_u32_e32 v2, 0xfff0c0, v4
	v_lshrrev_b32_e32 v2, 1, v2
	v_add_lshl_u32 v2, v2, s35, 9
	v_or3_b32 v2, v2, v5, s4
	v_lshl_add_u32 v2, v2, 1, v235
	s_mov_b64 s[14:15], 0

.LBB0_566:
	s_waitcnt vmcnt(0)
	v_mov_b32_e32 v0, v228
	s_barrier
	s_nop 0
	v_cmp_eq_u32_e32 vcc, 0, v0
	s_and_saveexec_b64 s[8:9], vcc
	v_readlane_b32 s19, v255, 27
	s_cbranch_execz .LBB0_568
	v_readlane_b32 s4, v255, 18
	v_readlane_b32 s5, v255, 19
	s_and_b32 s2, s4, 7
	s_lshl_b32 s2, s2, 4
	s_lshr_b32 s4, s4, 3
	s_or_b32 s4, s4, s2
	s_ashr_i32 s4, s4, 3
	s_ashr_i32 s5, s4, 31
	s_lshl_b64 s[4:5], s[4:5], 2
	s_add_u32 s4, s19, s4
	v_readlane_b32 s2, v255, 26
	s_addc_u32 s5, s2, s5
	buffer_wbl2 sc1
	s_waitcnt vmcnt(0)
	v_mov_b64_e32 v[0:1], s[4:5]
	flat_atomic_add v[0:1], v230
